# P5 mid-K: non-temporal hint on the read-once gate_a loads
# speedup vs baseline: 1.0047x; 1.0047x over previous
.LBB0_703:
	s_cmpk_lg_i32 s48, 0x400
	s_cbranch_scc1 .LBB0_702
	v_lshlrev_b32_e32 v208, 12, v155
	v_lshl_add_u32 v208, v154, 1, v208
	s_mov_b64 s[20:21], s[26:27]
	global_load_dwordx4 v[168:171], v208, s[20:21] nt
	global_load_dwordx4 v[172:175], v208, s[20:21] offset:2048
	global_load_dwordx4 v[176:179], v208, s[20:21] offset:64 nt
	global_load_dwordx4 v[180:183], v208, s[20:21] offset:2112
	s_add_u32 s20, s26, 0x10000
	s_addc_u32 s21, s27, 0
	global_load_dwordx4 v[184:187], v208, s[20:21] nt
	global_load_dwordx4 v[188:191], v208, s[20:21] offset:2048
	global_load_dwordx4 v[192:195], v208, s[20:21] offset:64 nt
	global_load_dwordx4 v[196:199], v208, s[20:21] offset:2112
	s_add_u32 s20, s26, 0x20000
	s_addc_u32 s21, s27, 0
	global_load_dwordx4 v[200:203], v208, s[20:21] nt
	global_load_dwordx4 v[204:207], v208, s[20:21] offset:2048
	global_load_dwordx4 v[218:221], v208, s[20:21] offset:64 nt
	global_load_dwordx4 v[222:225], v208, s[20:21] offset:2112
	s_add_u32 s20, s26, 0x30000
	s_addc_u32 s21, s27, 0
	global_load_dwordx4 v[226:229], v208, s[20:21] nt
	global_load_dwordx4 v[230:233], v208, s[20:21] offset:2048
	global_load_dwordx4 v[234:237], v208, s[20:21] offset:64 nt
	global_load_dwordx4 v[238:241], v208, s[20:21] offset:2112
	s_waitcnt vmcnt(14)
	v_lshlrev_b32_e32 v128, 16, v172
	v_and_b32_e32 v129, 0xffff0000, v172
	v_lshlrev_b32_e32 v130, 16, v173
	v_and_b32_e32 v131, 0xffff0000, v173
	v_lshlrev_b32_e32 v132, 16, v174
	v_and_b32_e32 v133, 0xffff0000, v174
	v_lshlrev_b32_e32 v134, 16, v175
	v_and_b32_e32 v135, 0xffff0000, v175
	v_max_f32_e32 v128, 0xda24260, v128
	v_max_f32_e32 v129, 0xda24260, v129
	v_max_f32_e32 v130, 0xda24260, v130
	v_max_f32_e32 v131, 0xda24260, v131
	v_max_f32_e32 v132, 0xda24260, v132
	v_max_f32_e32 v133, 0xda24260, v133
	v_max_f32_e32 v134, 0xda24260, v134
	v_max_f32_e32 v135, 0xda24260, v135
	v_rcp_f32_e32 v128, v128
	v_rcp_f32_e32 v129, v129
	v_rcp_f32_e32 v130, v130
	v_rcp_f32_e32 v131, v131
	v_rcp_f32_e32 v132, v132
	v_rcp_f32_e32 v133, v133
	v_rcp_f32_e32 v134, v134
	v_rcp_f32_e32 v135, v135
	v_and_b32_e32 v175, 0xffff0000, v171
	v_lshlrev_b32_e32 v174, 16, v171
	v_and_b32_e32 v173, 0xffff0000, v170
	v_lshlrev_b32_e32 v172, 16, v170
	v_and_b32_e32 v171, 0xffff0000, v169
	v_lshlrev_b32_e32 v170, 16, v169
	v_and_b32_e32 v169, 0xffff0000, v168
	v_lshlrev_b32_e32 v168, 16, v168
	v_pk_mul_f32 v[168:169], v[128:129], v[168:169]
	v_pk_mul_f32 v[170:171], v[130:131], v[170:171]
	v_pk_mul_f32 v[172:173], v[132:133], v[172:173]
	v_pk_mul_f32 v[174:175], v[134:135], v[174:175]
	v_pk_mul_f32 v[124:125], v[124:125], v[168:169]
	v_pk_mul_f32 v[126:127], v[126:127], v[170:171]
	v_pk_mul_f32 v[120:121], v[120:121], v[172:173]
	v_pk_mul_f32 v[122:123], v[122:123], v[174:175]
	s_add_u32 s20, s26, 0x80000
	s_addc_u32 s21, s27, 0
	global_load_dwordx4 v[168:171], v208, s[20:21] nt
	global_load_dwordx4 v[172:175], v208, s[20:21] offset:2048
	s_waitcnt vmcnt(14)
	v_lshlrev_b32_e32 v128, 16, v180
	v_and_b32_e32 v129, 0xffff0000, v180
	v_lshlrev_b32_e32 v130, 16, v181
	v_and_b32_e32 v131, 0xffff0000, v181
	v_lshlrev_b32_e32 v132, 16, v182
	v_and_b32_e32 v133, 0xffff0000, v182
	v_lshlrev_b32_e32 v134, 16, v183
	v_and_b32_e32 v135, 0xffff0000, v183
	v_max_f32_e32 v128, 0xda24260, v128
	v_max_f32_e32 v129, 0xda24260, v129
	v_max_f32_e32 v130, 0xda24260, v130
	v_max_f32_e32 v131, 0xda24260, v131
	v_max_f32_e32 v132, 0xda24260, v132
	v_max_f32_e32 v133, 0xda24260, v133
	v_max_f32_e32 v134, 0xda24260, v134
	v_max_f32_e32 v135, 0xda24260, v135
	v_rcp_f32_e32 v128, v128
	v_rcp_f32_e32 v129, v129
	v_rcp_f32_e32 v130, v130
	v_rcp_f32_e32 v131, v131
	v_rcp_f32_e32 v132, v132
	v_rcp_f32_e32 v133, v133
	v_rcp_f32_e32 v134, v134
	v_rcp_f32_e32 v135, v135
	v_and_b32_e32 v183, 0xffff0000, v179
	v_lshlrev_b32_e32 v182, 16, v179
	v_and_b32_e32 v181, 0xffff0000, v178
	v_lshlrev_b32_e32 v180, 16, v178
	v_and_b32_e32 v179, 0xffff0000, v177
	v_lshlrev_b32_e32 v178, 16, v177
	v_and_b32_e32 v177, 0xffff0000, v176
	v_lshlrev_b32_e32 v176, 16, v176
	v_pk_mul_f32 v[176:177], v[128:129], v[176:177]
	v_pk_mul_f32 v[178:179], v[130:131], v[178:179]
	v_pk_mul_f32 v[180:181], v[132:133], v[180:181]
	v_pk_mul_f32 v[182:183], v[134:135], v[182:183]
	v_pk_mul_f32 v[116:117], v[116:117], v[176:177]
	v_pk_mul_f32 v[118:119], v[118:119], v[178:179]
	v_pk_mul_f32 v[112:113], v[112:113], v[180:181]
	v_pk_mul_f32 v[114:115], v[114:115], v[182:183]
	global_load_dwordx4 v[176:179], v208, s[20:21] offset:64 nt
	global_load_dwordx4 v[180:183], v208, s[20:21] offset:2112
	s_waitcnt vmcnt(14)
	v_lshlrev_b32_e32 v128, 16, v188
	v_and_b32_e32 v129, 0xffff0000, v188
	v_lshlrev_b32_e32 v130, 16, v189
	v_and_b32_e32 v131, 0xffff0000, v189
	v_lshlrev_b32_e32 v132, 16, v190
	v_and_b32_e32 v133, 0xffff0000, v190
	v_lshlrev_b32_e32 v134, 16, v191
	v_and_b32_e32 v135, 0xffff0000, v191
	v_max_f32_e32 v128, 0xda24260, v128
	v_max_f32_e32 v129, 0xda24260, v129
	v_max_f32_e32 v130, 0xda24260, v130
	v_max_f32_e32 v131, 0xda24260, v131
	v_max_f32_e32 v132, 0xda24260, v132
	v_max_f32_e32 v133, 0xda24260, v133
	v_max_f32_e32 v134, 0xda24260, v134
	v_max_f32_e32 v135, 0xda24260, v135
	v_rcp_f32_e32 v128, v128
	v_rcp_f32_e32 v129, v129
	v_rcp_f32_e32 v130, v130
	v_rcp_f32_e32 v131, v131
	v_rcp_f32_e32 v132, v132
	v_rcp_f32_e32 v133, v133
	v_rcp_f32_e32 v134, v134
	v_rcp_f32_e32 v135, v135
	v_and_b32_e32 v191, 0xffff0000, v187
	v_lshlrev_b32_e32 v190, 16, v187
	v_and_b32_e32 v189, 0xffff0000, v186
	v_lshlrev_b32_e32 v188, 16, v186
	v_and_b32_e32 v187, 0xffff0000, v185
	v_lshlrev_b32_e32 v186, 16, v185
	v_and_b32_e32 v185, 0xffff0000, v184
	v_lshlrev_b32_e32 v184, 16, v184
	v_pk_mul_f32 v[184:185], v[128:129], v[184:185]
	v_pk_mul_f32 v[186:187], v[130:131], v[186:187]
	v_pk_mul_f32 v[188:189], v[132:133], v[188:189]
	v_pk_mul_f32 v[190:191], v[134:135], v[190:191]
	v_pk_mul_f32 v[108:109], v[108:109], v[184:185]
	v_pk_mul_f32 v[110:111], v[110:111], v[186:187]
	v_pk_mul_f32 v[104:105], v[104:105], v[188:189]
	v_pk_mul_f32 v[106:107], v[106:107], v[190:191]
	s_add_u32 s20, s26, 0x90000
	s_addc_u32 s21, s27, 0
	global_load_dwordx4 v[184:187], v208, s[20:21] nt
	global_load_dwordx4 v[188:191], v208, s[20:21] offset:2048
	s_waitcnt vmcnt(14)
	v_lshlrev_b32_e32 v128, 16, v196
	v_and_b32_e32 v129, 0xffff0000, v196
	v_lshlrev_b32_e32 v130, 16, v197
	v_and_b32_e32 v131, 0xffff0000, v197
	v_lshlrev_b32_e32 v132, 16, v198
	v_and_b32_e32 v133, 0xffff0000, v198
	v_lshlrev_b32_e32 v134, 16, v199
	v_and_b32_e32 v135, 0xffff0000, v199
	v_max_f32_e32 v128, 0xda24260, v128
	v_max_f32_e32 v129, 0xda24260, v129
	v_max_f32_e32 v130, 0xda24260, v130
	v_max_f32_e32 v131, 0xda24260, v131
	v_max_f32_e32 v132, 0xda24260, v132
	v_max_f32_e32 v133, 0xda24260, v133
	v_max_f32_e32 v134, 0xda24260, v134
	v_max_f32_e32 v135, 0xda24260, v135
	v_rcp_f32_e32 v128, v128
	v_rcp_f32_e32 v129, v129
	v_rcp_f32_e32 v130, v130
	v_rcp_f32_e32 v131, v131
	v_rcp_f32_e32 v132, v132
	v_rcp_f32_e32 v133, v133
	v_rcp_f32_e32 v134, v134
	v_rcp_f32_e32 v135, v135
	v_and_b32_e32 v199, 0xffff0000, v195
	v_lshlrev_b32_e32 v198, 16, v195
	v_and_b32_e32 v197, 0xffff0000, v194
	v_lshlrev_b32_e32 v196, 16, v194
	v_and_b32_e32 v195, 0xffff0000, v193
	v_lshlrev_b32_e32 v194, 16, v193
	v_and_b32_e32 v193, 0xffff0000, v192
	v_lshlrev_b32_e32 v192, 16, v192
	v_pk_mul_f32 v[192:193], v[128:129], v[192:193]
	v_pk_mul_f32 v[194:195], v[130:131], v[194:195]
	v_pk_mul_f32 v[196:197], v[132:133], v[196:197]
	v_pk_mul_f32 v[198:199], v[134:135], v[198:199]
	v_pk_mul_f32 v[100:101], v[100:101], v[192:193]
	v_pk_mul_f32 v[102:103], v[102:103], v[194:195]
	v_pk_mul_f32 v[96:97], v[96:97], v[196:197]
	v_pk_mul_f32 v[98:99], v[98:99], v[198:199]
	global_load_dwordx4 v[192:195], v208, s[20:21] offset:64 nt
	global_load_dwordx4 v[196:199], v208, s[20:21] offset:2112
	s_waitcnt vmcnt(14)
	v_lshlrev_b32_e32 v128, 16, v204
	v_and_b32_e32 v129, 0xffff0000, v204
	v_lshlrev_b32_e32 v130, 16, v205
	v_and_b32_e32 v131, 0xffff0000, v205
	v_lshlrev_b32_e32 v132, 16, v206
	v_and_b32_e32 v133, 0xffff0000, v206
	v_lshlrev_b32_e32 v134, 16, v207
	v_and_b32_e32 v135, 0xffff0000, v207
	v_max_f32_e32 v128, 0xda24260, v128
	v_max_f32_e32 v129, 0xda24260, v129
	v_max_f32_e32 v130, 0xda24260, v130
	v_max_f32_e32 v131, 0xda24260, v131
	v_max_f32_e32 v132, 0xda24260, v132
	v_max_f32_e32 v133, 0xda24260, v133
	v_max_f32_e32 v134, 0xda24260, v134
	v_max_f32_e32 v135, 0xda24260, v135
	v_rcp_f32_e32 v128, v128
	v_rcp_f32_e32 v129, v129
	v_rcp_f32_e32 v130, v130
	v_rcp_f32_e32 v131, v131
	v_rcp_f32_e32 v132, v132
	v_rcp_f32_e32 v133, v133
	v_rcp_f32_e32 v134, v134
	v_rcp_f32_e32 v135, v135
	v_and_b32_e32 v207, 0xffff0000, v203
	v_lshlrev_b32_e32 v206, 16, v203
	v_and_b32_e32 v205, 0xffff0000, v202
	v_lshlrev_b32_e32 v204, 16, v202
	v_and_b32_e32 v203, 0xffff0000, v201
	v_lshlrev_b32_e32 v202, 16, v201
	v_and_b32_e32 v201, 0xffff0000, v200
	v_lshlrev_b32_e32 v200, 16, v200
	v_pk_mul_f32 v[200:201], v[128:129], v[200:201]
	v_pk_mul_f32 v[202:203], v[130:131], v[202:203]
	v_pk_mul_f32 v[204:205], v[132:133], v[204:205]
	v_pk_mul_f32 v[206:207], v[134:135], v[206:207]
	v_pk_mul_f32 v[92:93], v[92:93], v[200:201]
	v_pk_mul_f32 v[94:95], v[94:95], v[202:203]
	v_pk_mul_f32 v[88:89], v[88:89], v[204:205]
	v_pk_mul_f32 v[90:91], v[90:91], v[206:207]
	s_add_u32 s20, s26, 0xa0000
	s_addc_u32 s21, s27, 0
	global_load_dwordx4 v[200:203], v208, s[20:21] nt
	global_load_dwordx4 v[204:207], v208, s[20:21] offset:2048
	s_waitcnt vmcnt(14)
	v_lshlrev_b32_e32 v128, 16, v222
	v_and_b32_e32 v129, 0xffff0000, v222
	v_lshlrev_b32_e32 v130, 16, v223
	v_and_b32_e32 v131, 0xffff0000, v223
	v_lshlrev_b32_e32 v132, 16, v224
	v_and_b32_e32 v133, 0xffff0000, v224
	v_lshlrev_b32_e32 v134, 16, v225
	v_and_b32_e32 v135, 0xffff0000, v225
	v_max_f32_e32 v128, 0xda24260, v128
	v_max_f32_e32 v129, 0xda24260, v129
	v_max_f32_e32 v130, 0xda24260, v130
	v_max_f32_e32 v131, 0xda24260, v131
	v_max_f32_e32 v132, 0xda24260, v132
	v_max_f32_e32 v133, 0xda24260, v133
	v_max_f32_e32 v134, 0xda24260, v134
	v_max_f32_e32 v135, 0xda24260, v135
	v_rcp_f32_e32 v128, v128
	v_rcp_f32_e32 v129, v129
	v_rcp_f32_e32 v130, v130
	v_rcp_f32_e32 v131, v131
	v_rcp_f32_e32 v132, v132
	v_rcp_f32_e32 v133, v133
	v_rcp_f32_e32 v134, v134
	v_rcp_f32_e32 v135, v135
	v_and_b32_e32 v225, 0xffff0000, v221
	v_lshlrev_b32_e32 v224, 16, v221
	v_and_b32_e32 v223, 0xffff0000, v220
	v_lshlrev_b32_e32 v222, 16, v220
	v_and_b32_e32 v221, 0xffff0000, v219
	v_lshlrev_b32_e32 v220, 16, v219
	v_and_b32_e32 v219, 0xffff0000, v218
	v_lshlrev_b32_e32 v218, 16, v218
	v_pk_mul_f32 v[218:219], v[128:129], v[218:219]
	v_pk_mul_f32 v[220:221], v[130:131], v[220:221]
	v_pk_mul_f32 v[222:223], v[132:133], v[222:223]
	v_pk_mul_f32 v[224:225], v[134:135], v[224:225]
	v_pk_mul_f32 v[84:85], v[84:85], v[218:219]
	v_pk_mul_f32 v[86:87], v[86:87], v[220:221]
	v_pk_mul_f32 v[80:81], v[80:81], v[222:223]
	v_pk_mul_f32 v[82:83], v[82:83], v[224:225]
	global_load_dwordx4 v[218:221], v208, s[20:21] offset:64 nt
	global_load_dwordx4 v[222:225], v208, s[20:21] offset:2112
	s_waitcnt vmcnt(14)
	v_lshlrev_b32_e32 v128, 16, v230
	v_and_b32_e32 v129, 0xffff0000, v230
	v_lshlrev_b32_e32 v130, 16, v231
	v_and_b32_e32 v131, 0xffff0000, v231
	v_lshlrev_b32_e32 v132, 16, v232
	v_and_b32_e32 v133, 0xffff0000, v232
	v_lshlrev_b32_e32 v134, 16, v233
	v_and_b32_e32 v135, 0xffff0000, v233
	v_max_f32_e32 v128, 0xda24260, v128
	v_max_f32_e32 v129, 0xda24260, v129
	v_max_f32_e32 v130, 0xda24260, v130
	v_max_f32_e32 v131, 0xda24260, v131
	v_max_f32_e32 v132, 0xda24260, v132
	v_max_f32_e32 v133, 0xda24260, v133
	v_max_f32_e32 v134, 0xda24260, v134
	v_max_f32_e32 v135, 0xda24260, v135
	v_rcp_f32_e32 v128, v128
	v_rcp_f32_e32 v129, v129
	v_rcp_f32_e32 v130, v130
	v_rcp_f32_e32 v131, v131
	v_rcp_f32_e32 v132, v132
	v_rcp_f32_e32 v133, v133
	v_rcp_f32_e32 v134, v134
	v_rcp_f32_e32 v135, v135
	v_and_b32_e32 v233, 0xffff0000, v229
	v_lshlrev_b32_e32 v232, 16, v229
	v_and_b32_e32 v231, 0xffff0000, v228
	v_lshlrev_b32_e32 v230, 16, v228
	v_and_b32_e32 v229, 0xffff0000, v227
	v_lshlrev_b32_e32 v228, 16, v227
	v_and_b32_e32 v227, 0xffff0000, v226
	v_lshlrev_b32_e32 v226, 16, v226
	v_pk_mul_f32 v[226:227], v[128:129], v[226:227]
	v_pk_mul_f32 v[228:229], v[130:131], v[228:229]
	v_pk_mul_f32 v[230:231], v[132:133], v[230:231]
	v_pk_mul_f32 v[232:233], v[134:135], v[232:233]
	v_pk_mul_f32 v[76:77], v[76:77], v[226:227]
	v_pk_mul_f32 v[78:79], v[78:79], v[228:229]
	v_pk_mul_f32 v[72:73], v[72:73], v[230:231]
	v_pk_mul_f32 v[74:75], v[74:75], v[232:233]
	s_add_u32 s20, s26, 0xb0000
	s_addc_u32 s21, s27, 0
	global_load_dwordx4 v[226:229], v208, s[20:21] nt
	global_load_dwordx4 v[230:233], v208, s[20:21] offset:2048
	s_waitcnt vmcnt(14)
	v_lshlrev_b32_e32 v128, 16, v238
	v_and_b32_e32 v129, 0xffff0000, v238
	v_lshlrev_b32_e32 v130, 16, v239
	v_and_b32_e32 v131, 0xffff0000, v239
	v_lshlrev_b32_e32 v132, 16, v240
	v_and_b32_e32 v133, 0xffff0000, v240
	v_lshlrev_b32_e32 v134, 16, v241
	v_and_b32_e32 v135, 0xffff0000, v241
	v_max_f32_e32 v128, 0xda24260, v128
	v_max_f32_e32 v129, 0xda24260, v129
	v_max_f32_e32 v130, 0xda24260, v130
	v_max_f32_e32 v131, 0xda24260, v131
	v_max_f32_e32 v132, 0xda24260, v132
	v_max_f32_e32 v133, 0xda24260, v133
	v_max_f32_e32 v134, 0xda24260, v134
	v_max_f32_e32 v135, 0xda24260, v135
	v_rcp_f32_e32 v128, v128
	v_rcp_f32_e32 v129, v129
	v_rcp_f32_e32 v130, v130
	v_rcp_f32_e32 v131, v131
	v_rcp_f32_e32 v132, v132
	v_rcp_f32_e32 v133, v133
	v_rcp_f32_e32 v134, v134
	v_rcp_f32_e32 v135, v135
	v_and_b32_e32 v241, 0xffff0000, v237
	v_lshlrev_b32_e32 v240, 16, v237
	v_and_b32_e32 v239, 0xffff0000, v236
	v_lshlrev_b32_e32 v238, 16, v236
	v_and_b32_e32 v237, 0xffff0000, v235
	v_lshlrev_b32_e32 v236, 16, v235
	v_and_b32_e32 v235, 0xffff0000, v234
	v_lshlrev_b32_e32 v234, 16, v234
	v_pk_mul_f32 v[234:235], v[128:129], v[234:235]
	v_pk_mul_f32 v[236:237], v[130:131], v[236:237]
	v_pk_mul_f32 v[238:239], v[132:133], v[238:239]
	v_pk_mul_f32 v[240:241], v[134:135], v[240:241]
	v_pk_mul_f32 v[68:69], v[68:69], v[234:235]
	v_pk_mul_f32 v[70:71], v[70:71], v[236:237]
	v_pk_mul_f32 v[64:65], v[64:65], v[238:239]
	v_pk_mul_f32 v[66:67], v[66:67], v[240:241]
	global_load_dwordx4 v[234:237], v208, s[20:21] offset:64 nt
	global_load_dwordx4 v[238:241], v208, s[20:21] offset:2112
	s_waitcnt vmcnt(14)
	v_lshlrev_b32_e32 v128, 16, v172
	v_and_b32_e32 v129, 0xffff0000, v172
	v_lshlrev_b32_e32 v130, 16, v173
	v_and_b32_e32 v131, 0xffff0000, v173
	v_lshlrev_b32_e32 v132, 16, v174
	v_and_b32_e32 v133, 0xffff0000, v174
	v_lshlrev_b32_e32 v134, 16, v175
	v_and_b32_e32 v135, 0xffff0000, v175
	v_max_f32_e32 v128, 0xda24260, v128
	v_max_f32_e32 v129, 0xda24260, v129
	v_max_f32_e32 v130, 0xda24260, v130
	v_max_f32_e32 v131, 0xda24260, v131
	v_max_f32_e32 v132, 0xda24260, v132
	v_max_f32_e32 v133, 0xda24260, v133
	v_max_f32_e32 v134, 0xda24260, v134
	v_max_f32_e32 v135, 0xda24260, v135
	v_rcp_f32_e32 v128, v128
	v_rcp_f32_e32 v129, v129
	v_rcp_f32_e32 v130, v130
	v_rcp_f32_e32 v131, v131
	v_rcp_f32_e32 v132, v132
	v_rcp_f32_e32 v133, v133
	v_rcp_f32_e32 v134, v134
	v_rcp_f32_e32 v135, v135
	v_and_b32_e32 v175, 0xffff0000, v171
	v_lshlrev_b32_e32 v174, 16, v171
	v_and_b32_e32 v173, 0xffff0000, v170
	v_lshlrev_b32_e32 v172, 16, v170
	v_and_b32_e32 v171, 0xffff0000, v169
	v_lshlrev_b32_e32 v170, 16, v169
	v_and_b32_e32 v169, 0xffff0000, v168
	v_lshlrev_b32_e32 v168, 16, v168
	v_pk_mul_f32 v[168:169], v[128:129], v[168:169]
	v_pk_mul_f32 v[170:171], v[130:131], v[170:171]
	v_pk_mul_f32 v[172:173], v[132:133], v[172:173]
	v_pk_mul_f32 v[174:175], v[134:135], v[174:175]
	v_pk_mul_f32 v[60:61], v[60:61], v[168:169]
	v_pk_mul_f32 v[62:63], v[62:63], v[170:171]
	v_pk_mul_f32 v[56:57], v[56:57], v[172:173]
	v_pk_mul_f32 v[58:59], v[58:59], v[174:175]
	s_waitcnt vmcnt(12)
	v_lshlrev_b32_e32 v128, 16, v180
	v_and_b32_e32 v129, 0xffff0000, v180
	v_lshlrev_b32_e32 v130, 16, v181
	v_and_b32_e32 v131, 0xffff0000, v181
	v_lshlrev_b32_e32 v132, 16, v182
	v_and_b32_e32 v133, 0xffff0000, v182
	v_lshlrev_b32_e32 v134, 16, v183
	v_and_b32_e32 v135, 0xffff0000, v183
	v_max_f32_e32 v128, 0xda24260, v128
	v_max_f32_e32 v129, 0xda24260, v129
	v_max_f32_e32 v130, 0xda24260, v130
	v_max_f32_e32 v131, 0xda24260, v131
	v_max_f32_e32 v132, 0xda24260, v132
	v_max_f32_e32 v133, 0xda24260, v133
	v_max_f32_e32 v134, 0xda24260, v134
	v_max_f32_e32 v135, 0xda24260, v135
	v_rcp_f32_e32 v128, v128
	v_rcp_f32_e32 v129, v129
	v_rcp_f32_e32 v130, v130
	v_rcp_f32_e32 v131, v131
	v_rcp_f32_e32 v132, v132
	v_rcp_f32_e32 v133, v133
	v_rcp_f32_e32 v134, v134
	v_rcp_f32_e32 v135, v135
	v_and_b32_e32 v183, 0xffff0000, v179
	v_lshlrev_b32_e32 v182, 16, v179
	v_and_b32_e32 v181, 0xffff0000, v178
	v_lshlrev_b32_e32 v180, 16, v178
	v_and_b32_e32 v179, 0xffff0000, v177
	v_lshlrev_b32_e32 v178, 16, v177
	v_and_b32_e32 v177, 0xffff0000, v176
	v_lshlrev_b32_e32 v176, 16, v176
	v_pk_mul_f32 v[176:177], v[128:129], v[176:177]
	v_pk_mul_f32 v[178:179], v[130:131], v[178:179]
	v_pk_mul_f32 v[180:181], v[132:133], v[180:181]
	v_pk_mul_f32 v[182:183], v[134:135], v[182:183]
	v_pk_mul_f32 v[52:53], v[52:53], v[176:177]
	v_pk_mul_f32 v[54:55], v[54:55], v[178:179]
	v_pk_mul_f32 v[48:49], v[48:49], v[180:181]
	v_pk_mul_f32 v[50:51], v[50:51], v[182:183]
	s_waitcnt vmcnt(10)
	v_lshlrev_b32_e32 v128, 16, v188
	v_and_b32_e32 v129, 0xffff0000, v188
	v_lshlrev_b32_e32 v130, 16, v189
	v_and_b32_e32 v131, 0xffff0000, v189
	v_lshlrev_b32_e32 v132, 16, v190
	v_and_b32_e32 v133, 0xffff0000, v190
	v_lshlrev_b32_e32 v134, 16, v191
	v_and_b32_e32 v135, 0xffff0000, v191
	v_max_f32_e32 v128, 0xda24260, v128
	v_max_f32_e32 v129, 0xda24260, v129
	v_max_f32_e32 v130, 0xda24260, v130
	v_max_f32_e32 v131, 0xda24260, v131
	v_max_f32_e32 v132, 0xda24260, v132
	v_max_f32_e32 v133, 0xda24260, v133
	v_max_f32_e32 v134, 0xda24260, v134
	v_max_f32_e32 v135, 0xda24260, v135
	v_rcp_f32_e32 v128, v128
	v_rcp_f32_e32 v129, v129
	v_rcp_f32_e32 v130, v130
	v_rcp_f32_e32 v131, v131
	v_rcp_f32_e32 v132, v132
	v_rcp_f32_e32 v133, v133
	v_rcp_f32_e32 v134, v134
	v_rcp_f32_e32 v135, v135
	v_and_b32_e32 v191, 0xffff0000, v187
	v_lshlrev_b32_e32 v190, 16, v187
	v_and_b32_e32 v189, 0xffff0000, v186
	v_lshlrev_b32_e32 v188, 16, v186
	v_and_b32_e32 v187, 0xffff0000, v185
	v_lshlrev_b32_e32 v186, 16, v185
	v_and_b32_e32 v185, 0xffff0000, v184
	v_lshlrev_b32_e32 v184, 16, v184
	v_pk_mul_f32 v[184:185], v[128:129], v[184:185]
	v_pk_mul_f32 v[186:187], v[130:131], v[186:187]
	v_pk_mul_f32 v[188:189], v[132:133], v[188:189]
	v_pk_mul_f32 v[190:191], v[134:135], v[190:191]
	v_pk_mul_f32 v[44:45], v[44:45], v[184:185]
	v_pk_mul_f32 v[46:47], v[46:47], v[186:187]
	v_pk_mul_f32 v[40:41], v[40:41], v[188:189]
	v_pk_mul_f32 v[42:43], v[42:43], v[190:191]
	s_waitcnt vmcnt(8)
	v_lshlrev_b32_e32 v128, 16, v196
	v_and_b32_e32 v129, 0xffff0000, v196
	v_lshlrev_b32_e32 v130, 16, v197
	v_and_b32_e32 v131, 0xffff0000, v197
	v_lshlrev_b32_e32 v132, 16, v198
	v_and_b32_e32 v133, 0xffff0000, v198
	v_lshlrev_b32_e32 v134, 16, v199
	v_and_b32_e32 v135, 0xffff0000, v199
	v_max_f32_e32 v128, 0xda24260, v128
	v_max_f32_e32 v129, 0xda24260, v129
	v_max_f32_e32 v130, 0xda24260, v130
	v_max_f32_e32 v131, 0xda24260, v131
	v_max_f32_e32 v132, 0xda24260, v132
	v_max_f32_e32 v133, 0xda24260, v133
	v_max_f32_e32 v134, 0xda24260, v134
	v_max_f32_e32 v135, 0xda24260, v135
	v_rcp_f32_e32 v128, v128
	v_rcp_f32_e32 v129, v129
	v_rcp_f32_e32 v130, v130
	v_rcp_f32_e32 v131, v131
	v_rcp_f32_e32 v132, v132
	v_rcp_f32_e32 v133, v133
	v_rcp_f32_e32 v134, v134
	v_rcp_f32_e32 v135, v135
	v_and_b32_e32 v199, 0xffff0000, v195
	v_lshlrev_b32_e32 v198, 16, v195
	v_and_b32_e32 v197, 0xffff0000, v194
	v_lshlrev_b32_e32 v196, 16, v194
	v_and_b32_e32 v195, 0xffff0000, v193
	v_lshlrev_b32_e32 v194, 16, v193
	v_and_b32_e32 v193, 0xffff0000, v192
	v_lshlrev_b32_e32 v192, 16, v192
	v_pk_mul_f32 v[192:193], v[128:129], v[192:193]
	v_pk_mul_f32 v[194:195], v[130:131], v[194:195]
	v_pk_mul_f32 v[196:197], v[132:133], v[196:197]
	v_pk_mul_f32 v[198:199], v[134:135], v[198:199]
	v_pk_mul_f32 v[36:37], v[36:37], v[192:193]
	v_pk_mul_f32 v[38:39], v[38:39], v[194:195]
	v_pk_mul_f32 v[32:33], v[32:33], v[196:197]
	v_pk_mul_f32 v[34:35], v[34:35], v[198:199]
	s_waitcnt vmcnt(6)
	v_lshlrev_b32_e32 v128, 16, v204
	v_and_b32_e32 v129, 0xffff0000, v204
	v_lshlrev_b32_e32 v130, 16, v205
	v_and_b32_e32 v131, 0xffff0000, v205
	v_lshlrev_b32_e32 v132, 16, v206
	v_and_b32_e32 v133, 0xffff0000, v206
	v_lshlrev_b32_e32 v134, 16, v207
	v_and_b32_e32 v135, 0xffff0000, v207
	v_max_f32_e32 v128, 0xda24260, v128
	v_max_f32_e32 v129, 0xda24260, v129
	v_max_f32_e32 v130, 0xda24260, v130
	v_max_f32_e32 v131, 0xda24260, v131
	v_max_f32_e32 v132, 0xda24260, v132
	v_max_f32_e32 v133, 0xda24260, v133
	v_max_f32_e32 v134, 0xda24260, v134
	v_max_f32_e32 v135, 0xda24260, v135
	v_rcp_f32_e32 v128, v128
	v_rcp_f32_e32 v129, v129
	v_rcp_f32_e32 v130, v130
	v_rcp_f32_e32 v131, v131
	v_rcp_f32_e32 v132, v132
	v_rcp_f32_e32 v133, v133
	v_rcp_f32_e32 v134, v134
	v_rcp_f32_e32 v135, v135
	v_and_b32_e32 v207, 0xffff0000, v203
	v_lshlrev_b32_e32 v206, 16, v203
	v_and_b32_e32 v205, 0xffff0000, v202
	v_lshlrev_b32_e32 v204, 16, v202
	v_and_b32_e32 v203, 0xffff0000, v201
	v_lshlrev_b32_e32 v202, 16, v201
	v_and_b32_e32 v201, 0xffff0000, v200
	v_lshlrev_b32_e32 v200, 16, v200
	v_pk_mul_f32 v[200:201], v[128:129], v[200:201]
	v_pk_mul_f32 v[202:203], v[130:131], v[202:203]
	v_pk_mul_f32 v[204:205], v[132:133], v[204:205]
	v_pk_mul_f32 v[206:207], v[134:135], v[206:207]
	v_pk_mul_f32 v[28:29], v[28:29], v[200:201]
	v_pk_mul_f32 v[30:31], v[30:31], v[202:203]
	v_pk_mul_f32 v[24:25], v[24:25], v[204:205]
	v_pk_mul_f32 v[26:27], v[26:27], v[206:207]
	s_waitcnt vmcnt(4)
	v_lshlrev_b32_e32 v128, 16, v222
	v_and_b32_e32 v129, 0xffff0000, v222
	v_lshlrev_b32_e32 v130, 16, v223
	v_and_b32_e32 v131, 0xffff0000, v223
	v_lshlrev_b32_e32 v132, 16, v224
	v_and_b32_e32 v133, 0xffff0000, v224
	v_lshlrev_b32_e32 v134, 16, v225
	v_and_b32_e32 v135, 0xffff0000, v225
	v_max_f32_e32 v128, 0xda24260, v128
	v_max_f32_e32 v129, 0xda24260, v129
	v_max_f32_e32 v130, 0xda24260, v130
	v_max_f32_e32 v131, 0xda24260, v131
	v_max_f32_e32 v132, 0xda24260, v132
	v_max_f32_e32 v133, 0xda24260, v133
	v_max_f32_e32 v134, 0xda24260, v134
	v_max_f32_e32 v135, 0xda24260, v135
	v_rcp_f32_e32 v128, v128
	v_rcp_f32_e32 v129, v129
	v_rcp_f32_e32 v130, v130
	v_rcp_f32_e32 v131, v131
	v_rcp_f32_e32 v132, v132
	v_rcp_f32_e32 v133, v133
	v_rcp_f32_e32 v134, v134
	v_rcp_f32_e32 v135, v135
	v_and_b32_e32 v225, 0xffff0000, v221
	v_lshlrev_b32_e32 v224, 16, v221
	v_and_b32_e32 v223, 0xffff0000, v220
	v_lshlrev_b32_e32 v222, 16, v220
	v_and_b32_e32 v221, 0xffff0000, v219
	v_lshlrev_b32_e32 v220, 16, v219
	v_and_b32_e32 v219, 0xffff0000, v218
	v_lshlrev_b32_e32 v218, 16, v218
	v_pk_mul_f32 v[218:219], v[128:129], v[218:219]
	v_pk_mul_f32 v[220:221], v[130:131], v[220:221]
	v_pk_mul_f32 v[222:223], v[132:133], v[222:223]
	v_pk_mul_f32 v[224:225], v[134:135], v[224:225]
	v_pk_mul_f32 v[20:21], v[20:21], v[218:219]
	v_pk_mul_f32 v[22:23], v[22:23], v[220:221]
	v_pk_mul_f32 v[16:17], v[16:17], v[222:223]
	v_pk_mul_f32 v[18:19], v[18:19], v[224:225]
	s_waitcnt vmcnt(2)
	v_lshlrev_b32_e32 v128, 16, v230
	v_and_b32_e32 v129, 0xffff0000, v230
	v_lshlrev_b32_e32 v130, 16, v231
	v_and_b32_e32 v131, 0xffff0000, v231
	v_lshlrev_b32_e32 v132, 16, v232
	v_and_b32_e32 v133, 0xffff0000, v232
	v_lshlrev_b32_e32 v134, 16, v233
	v_and_b32_e32 v135, 0xffff0000, v233
	v_max_f32_e32 v128, 0xda24260, v128
	v_max_f32_e32 v129, 0xda24260, v129
	v_max_f32_e32 v130, 0xda24260, v130
	v_max_f32_e32 v131, 0xda24260, v131
	v_max_f32_e32 v132, 0xda24260, v132
	v_max_f32_e32 v133, 0xda24260, v133
	v_max_f32_e32 v134, 0xda24260, v134
	v_max_f32_e32 v135, 0xda24260, v135
	v_rcp_f32_e32 v128, v128
	v_rcp_f32_e32 v129, v129
	v_rcp_f32_e32 v130, v130
	v_rcp_f32_e32 v131, v131
	v_rcp_f32_e32 v132, v132
	v_rcp_f32_e32 v133, v133
	v_rcp_f32_e32 v134, v134
	v_rcp_f32_e32 v135, v135
	v_and_b32_e32 v233, 0xffff0000, v229
	v_lshlrev_b32_e32 v232, 16, v229
	v_and_b32_e32 v231, 0xffff0000, v228
	v_lshlrev_b32_e32 v230, 16, v228
	v_and_b32_e32 v229, 0xffff0000, v227
	v_lshlrev_b32_e32 v228, 16, v227
	v_and_b32_e32 v227, 0xffff0000, v226
	v_lshlrev_b32_e32 v226, 16, v226
	v_pk_mul_f32 v[226:227], v[128:129], v[226:227]
	v_pk_mul_f32 v[228:229], v[130:131], v[228:229]
	v_pk_mul_f32 v[230:231], v[132:133], v[230:231]
	v_pk_mul_f32 v[232:233], v[134:135], v[232:233]
	v_pk_mul_f32 v[12:13], v[12:13], v[226:227]
	v_pk_mul_f32 v[14:15], v[14:15], v[228:229]
	v_pk_mul_f32 v[8:9], v[8:9], v[230:231]
	v_pk_mul_f32 v[10:11], v[10:11], v[232:233]
	s_waitcnt vmcnt(0)
	v_lshlrev_b32_e32 v128, 16, v238
	v_and_b32_e32 v129, 0xffff0000, v238
	v_lshlrev_b32_e32 v130, 16, v239
	v_and_b32_e32 v131, 0xffff0000, v239
	v_lshlrev_b32_e32 v132, 16, v240
	v_and_b32_e32 v133, 0xffff0000, v240
	v_lshlrev_b32_e32 v134, 16, v241
	v_and_b32_e32 v135, 0xffff0000, v241
	v_max_f32_e32 v128, 0xda24260, v128
	v_max_f32_e32 v129, 0xda24260, v129
	v_max_f32_e32 v130, 0xda24260, v130
	v_max_f32_e32 v131, 0xda24260, v131
	v_max_f32_e32 v132, 0xda24260, v132
	v_max_f32_e32 v133, 0xda24260, v133
	v_max_f32_e32 v134, 0xda24260, v134
	v_max_f32_e32 v135, 0xda24260, v135
	v_rcp_f32_e32 v128, v128
	v_rcp_f32_e32 v129, v129
	v_rcp_f32_e32 v130, v130
	v_rcp_f32_e32 v131, v131
	v_rcp_f32_e32 v132, v132
	v_rcp_f32_e32 v133, v133
	v_rcp_f32_e32 v134, v134
	v_rcp_f32_e32 v135, v135
	v_and_b32_e32 v241, 0xffff0000, v237
	v_lshlrev_b32_e32 v240, 16, v237
	v_and_b32_e32 v239, 0xffff0000, v236
	v_lshlrev_b32_e32 v238, 16, v236
	v_and_b32_e32 v237, 0xffff0000, v235
	v_lshlrev_b32_e32 v236, 16, v235
	v_and_b32_e32 v235, 0xffff0000, v234
	v_lshlrev_b32_e32 v234, 16, v234
	v_pk_mul_f32 v[234:235], v[128:129], v[234:235]
	v_pk_mul_f32 v[236:237], v[130:131], v[236:237]
	v_pk_mul_f32 v[238:239], v[132:133], v[238:239]
	v_pk_mul_f32 v[240:241], v[134:135], v[240:241]
	v_pk_mul_f32 v[4:5], v[4:5], v[234:235]
	v_pk_mul_f32 v[6:7], v[6:7], v[236:237]
	v_pk_mul_f32 v[0:1], v[0:1], v[238:239]
	v_pk_mul_f32 v[2:3], v[2:3], v[240:241]
	s_branch .LBB0_702
